# SB unmasked scan rewritten by hand: groups G,G+1 in aligned register pairs so the whole scan is v_pk_mul_f32 without pair-building moves (same association order), own PV tail
# speedup vs baseline: 1.0089x; 1.0089x over previous
; __device__ __forceinline__ float ex2(float x) { return __builtin_amdgcn_exp2f(x); }
; __device__ __forceinline__ float rcp(float x) { return __builtin_amdgcn_rcpf(x); }
; template <bool MK> __device__ __forceinline__ void sb_scan(f32x16& s0, f32x16& s1, int db, int hi, float& R) {
;             f32x16 k0, k1;
; #pragma unroll
;             for (int r = 0; r < 16; ++r) {
;                 const float e0 = ex2(fminf(s0[r], 80.f)), e1 = ex2(fminf(s1[r], 80.f));
;                 const float p0 = rcp(1.0f + e0), p1 = rcp(1.0f + e1);
;                 s0[r] = e0 * p0; s1[r] = e1 * p1;
;                 k0[r] = (!MK || KKOF(0, r) < db) ? p0 : 1.0f; k1[r] = (!MK || KKOF(1, r) < db) ? p1 : 1.0f;
;             }
;             float g4[8], pg[8], E[8];
; #pragma unroll
;             for (int k4 = 0; k4 < 4; ++k4) { g4[k4] = (k0[4 * k4] * k0[4 * k4 + 1]) * (k0[4 * k4 + 2] * k0[4 * k4 + 3]); g4[4 + k4] = (k1[4 * k4] * k1[4 * k4 + 1]) * (k1[4 * k4 + 2] * k1[4 * k4 + 3]); }
; #pragma unroll
;             for (int G = 0; G < 8; ++G) pg[G] = __shfl_xor(g4[G], 32);
;             E[7] = 1.0f;
; #pragma unroll
;             for (int G = 6; G >= 0; --G) E[G] = E[G + 1] * (g4[G + 1] * pg[G + 1]);
;             const float T = E[0] * (g4[0] * pg[0]);
.LBB0_626:
	s_andn2_b64 vcc, exec, s[24:25]
	s_cbranch_vccnz .LBB0_628
	v_exp_f32_e32 v124, v232
	v_exp_f32_e32 v126, v231
	v_exp_f32_e32 v128, v229
	v_exp_f32_e32 v130, v227
	v_exp_f32_e32 v125, v225
	v_exp_f32_e32 v127, v223
	v_exp_f32_e32 v129, v221
	v_exp_f32_e32 v131, v219
	v_add_f32_e32 v92, 1.0, v124
	v_add_f32_e32 v94, 1.0, v126
	v_add_f32_e32 v96, 1.0, v128
	v_add_f32_e32 v98, 1.0, v130
	v_add_f32_e32 v93, 1.0, v125
	v_add_f32_e32 v95, 1.0, v127
	v_add_f32_e32 v97, 1.0, v129
	v_add_f32_e32 v99, 1.0, v131
	v_rcp_f32_e32 v92, v92
	v_rcp_f32_e32 v94, v94
	v_rcp_f32_e32 v96, v96
	v_rcp_f32_e32 v98, v98
	v_rcp_f32_e32 v93, v93
	v_rcp_f32_e32 v95, v95
	v_rcp_f32_e32 v97, v97
	v_rcp_f32_e32 v99, v99
	v_exp_f32_e32 v132, v216
	v_exp_f32_e32 v134, v214
	v_exp_f32_e32 v136, v212
	v_exp_f32_e32 v138, v210
	v_exp_f32_e32 v133, v208
	v_exp_f32_e32 v135, v206
	v_exp_f32_e32 v137, v204
	v_exp_f32_e32 v139, v202
	v_add_f32_e32 v100, 1.0, v132
	v_add_f32_e32 v102, 1.0, v134
	v_add_f32_e32 v104, 1.0, v136
	v_add_f32_e32 v106, 1.0, v138
	v_add_f32_e32 v101, 1.0, v133
	v_add_f32_e32 v103, 1.0, v135
	v_add_f32_e32 v105, 1.0, v137
	v_add_f32_e32 v107, 1.0, v139
	v_rcp_f32_e32 v100, v100
	v_rcp_f32_e32 v102, v102
	v_rcp_f32_e32 v104, v104
	v_rcp_f32_e32 v106, v106
	v_rcp_f32_e32 v101, v101
	v_rcp_f32_e32 v103, v103
	v_rcp_f32_e32 v105, v105
	v_rcp_f32_e32 v107, v107
	v_exp_f32_e32 v140, v233
	v_exp_f32_e32 v142, v230
	v_exp_f32_e32 v144, v228
	v_exp_f32_e32 v146, v226
	v_exp_f32_e32 v141, v224
	v_exp_f32_e32 v143, v222
	v_exp_f32_e32 v145, v220
	v_exp_f32_e32 v147, v217
	v_add_f32_e32 v108, 1.0, v140
	v_add_f32_e32 v110, 1.0, v142
	v_add_f32_e32 v112, 1.0, v144
	v_add_f32_e32 v114, 1.0, v146
	v_add_f32_e32 v109, 1.0, v141
	v_add_f32_e32 v111, 1.0, v143
	v_add_f32_e32 v113, 1.0, v145
	v_add_f32_e32 v115, 1.0, v147
	v_rcp_f32_e32 v108, v108
	v_rcp_f32_e32 v110, v110
	v_rcp_f32_e32 v112, v112
	v_rcp_f32_e32 v114, v114
	v_rcp_f32_e32 v109, v109
	v_rcp_f32_e32 v111, v111
	v_rcp_f32_e32 v113, v113
	v_rcp_f32_e32 v115, v115
	v_exp_f32_e32 v148, v215
	v_exp_f32_e32 v150, v213
	v_exp_f32_e32 v152, v211
	v_exp_f32_e32 v154, v209
	v_exp_f32_e32 v149, v207
	v_exp_f32_e32 v151, v205
	v_exp_f32_e32 v153, v203
	v_exp_f32_e32 v155, v187
	v_add_f32_e32 v116, 1.0, v148
	v_add_f32_e32 v118, 1.0, v150
	v_add_f32_e32 v120, 1.0, v152
	v_add_f32_e32 v122, 1.0, v154
	v_add_f32_e32 v117, 1.0, v149
	v_add_f32_e32 v119, 1.0, v151
	v_add_f32_e32 v121, 1.0, v153
	v_add_f32_e32 v123, 1.0, v155
	v_rcp_f32_e32 v116, v116
	v_rcp_f32_e32 v118, v118
	v_rcp_f32_e32 v120, v120
	v_rcp_f32_e32 v122, v122
	v_rcp_f32_e32 v117, v117
	v_rcp_f32_e32 v119, v119
	v_rcp_f32_e32 v121, v121
	v_rcp_f32_e32 v123, v123
	v_pk_mul_f32 v[162:163], v[116:117], v[118:119]
	v_pk_mul_f32 v[42:43], v[120:121], v[122:123]
	v_pk_mul_f32 v[162:163], v[162:163], v[42:43]
	ds_bpermute_b32 v50, v201, v162
	ds_bpermute_b32 v51, v201, v163
	v_pk_mul_f32 v[160:161], v[108:109], v[110:111]
	v_pk_mul_f32 v[40:41], v[112:113], v[114:115]
	v_pk_mul_f32 v[160:161], v[160:161], v[40:41]
	ds_bpermute_b32 v48, v201, v160
	ds_bpermute_b32 v49, v201, v161
	v_pk_mul_f32 v[158:159], v[100:101], v[102:103]
	v_pk_mul_f32 v[38:39], v[104:105], v[106:107]
	v_pk_mul_f32 v[158:159], v[158:159], v[38:39]
	ds_bpermute_b32 v46, v201, v158
	ds_bpermute_b32 v47, v201, v159
	v_pk_mul_f32 v[156:157], v[92:93], v[94:95]
	v_pk_mul_f32 v[36:37], v[96:97], v[98:99]
	v_pk_mul_f32 v[156:157], v[156:157], v[36:37]
	ds_bpermute_b32 v44, v201, v156
	ds_bpermute_b32 v45, v201, v157
	v_pk_mul_f32 v[124:125], v[124:125], v[92:93]
	v_pk_mul_f32 v[126:127], v[126:127], v[94:95]
	v_pk_mul_f32 v[128:129], v[128:129], v[96:97]
	v_pk_mul_f32 v[130:131], v[130:131], v[98:99]
	v_pk_mul_f32 v[132:133], v[132:133], v[100:101]
	v_pk_mul_f32 v[134:135], v[134:135], v[102:103]
	v_pk_mul_f32 v[136:137], v[136:137], v[104:105]
	v_pk_mul_f32 v[138:139], v[138:139], v[106:107]
	v_pk_mul_f32 v[140:141], v[140:141], v[108:109]
	v_pk_mul_f32 v[142:143], v[142:143], v[110:111]
	v_pk_mul_f32 v[144:145], v[144:145], v[112:113]
	v_pk_mul_f32 v[146:147], v[146:147], v[114:115]
	v_pk_mul_f32 v[148:149], v[148:149], v[116:117]
	v_pk_mul_f32 v[150:151], v[150:151], v[118:119]
	v_pk_mul_f32 v[152:153], v[152:153], v[120:121]
	v_pk_mul_f32 v[154:155], v[154:155], v[122:123]
	s_waitcnt lgkmcnt(0)
; #define PACK_P(pw, s0, s1) do { _Pragma("unroll") for (int r_ = 0; r_ < 8; ++r_) { pw[r_] = pk2(s0[2 * r_], s0[2 * r_ + 1]); pw[8 + r_] = pk2(s1[2 * r_], s1[2 * r_ + 1]); } } while (0)
; template <bool MK> __device__ __forceinline__ void sb_scan(f32x16& s0, f32x16& s1, int db, int hi, float& R) {
;     ...
;             E[7] = 1.0f;
; #pragma unroll
;             for (int G = 6; G >= 0; --G) E[G] = E[G + 1] * (g4[G + 1] * pg[G + 1]);
;             const float T = E[0] * (g4[0] * pg[0]);
; #pragma unroll
;             for (int G = 0; G < 8; ++G) {
;                 const float base = R * E[G] * (hi == 0 ? pg[G] : 1.0f);
;                 const int k4 = G & 3;
;                 if (G < 4) {
;                     const float u3 = base, u2 = u3 * k0[4 * k4 + 3], u1 = u2 * k0[4 * k4 + 2], u0 = u1 * k0[4 * k4 + 1];
;                     s0[4 * k4 + 3] = (!MK || KKOF(0, 4 * k4 + 3) < db) ? s0[4 * k4 + 3] * u3 : 0.f;
;                     s0[4 * k4 + 2] = (!MK || KKOF(0, 4 * k4 + 2) < db) ? s0[4 * k4 + 2] * u2 : 0.f;
;                     s0[4 * k4 + 1] = (!MK || KKOF(0, 4 * k4 + 1) < db) ? s0[4 * k4 + 1] * u1 : 0.f;
;                     s0[4 * k4 + 0] = (!MK || KKOF(0, 4 * k4 + 0) < db) ? s0[4 * k4 + 0] * u0 : 0.f;
;                 } else {
;                     const float u3 = base, u2 = u3 * k1[4 * k4 + 3], u1 = u2 * k1[4 * k4 + 2], u0 = u1 * k1[4 * k4 + 1];
;                     s1[4 * k4 + 3] = (!MK || KKOF(1, 4 * k4 + 3) < db) ? s1[4 * k4 + 3] * u3 : 0.f;
;                     s1[4 * k4 + 2] = (!MK || KKOF(1, 4 * k4 + 2) < db) ? s1[4 * k4 + 2] * u2 : 0.f;
;                     s1[4 * k4 + 1] = (!MK || KKOF(1, 4 * k4 + 1) < db) ? s1[4 * k4 + 1] * u1 : 0.f;
;                     s1[4 * k4 + 0] = (!MK || KKOF(1, 4 * k4 + 0) < db) ? s1[4 * k4 + 0] * u0 : 0.f;
;                 }
;             }
;             R *= T;
; __device__ __forceinline__ void sb_unit(const Params& p, LAS unsigned char* lds, int b, int hp, int qb, int tid, int lane, int wave) {
;     ...
;             unsigned pw[16]; PACK_P(pw, s0, s1);
;             pv_tile_tr(stg + 8192, pw, tra, o0, o1);
;             dead = __all(R < 1.0e-44f);
	v_add3_u32 v165, s4, v182, v183
	v_add_u32_e32 v86, v165, v184
	v_add_u32_e32 v165, v165, v185
	ds_read_b64_tr_b16 v[202:203], v86 offset:8192
	ds_read_b64_tr_b16 v[204:205], v86 offset:9216
	ds_read_b64_tr_b16 v[206:207], v165 offset:8192
	ds_read_b64_tr_b16 v[208:209], v165 offset:9216
	ds_read_b64_tr_b16 v[210:211], v86 offset:10240
	ds_read_b64_tr_b16 v[212:213], v86 offset:11264
	ds_read_b64_tr_b16 v[214:215], v165 offset:10240
	ds_read_b64_tr_b16 v[216:217], v165 offset:11264
	v_pk_mul_f32 v[162:163], v[162:163], v[50:51]
	v_pk_mul_f32 v[160:161], v[160:161], v[48:49]
	v_pk_mul_f32 v[158:159], v[158:159], v[46:47]
	v_pk_mul_f32 v[156:157], v[156:157], v[44:45]
	v_mov_b32_e32 v42, v163
	v_mov_b32_e32 v43, 1.0
	v_mul_f32_e32 v41, v42, v162
	v_mul_f32_e32 v40, v41, v161
	v_mul_f32_e32 v39, v40, v160
	v_mul_f32_e32 v38, v39, v159
	v_mul_f32_e32 v37, v38, v158
	v_mul_f32_e32 v36, v37, v157
	v_mul_f32_e32 v164, v36, v156
	v_cndmask_b32_e64 v44, 1.0, v44, s[18:19]
	v_cndmask_b32_e64 v45, 1.0, v45, s[18:19]
	v_cndmask_b32_e64 v46, 1.0, v46, s[18:19]
	v_cndmask_b32_e64 v47, 1.0, v47, s[18:19]
	v_cndmask_b32_e64 v48, 1.0, v48, s[18:19]
	v_cndmask_b32_e64 v49, 1.0, v49, s[18:19]
	v_cndmask_b32_e64 v50, 1.0, v50, s[18:19]
	v_cndmask_b32_e64 v51, 1.0, v51, s[18:19]
	v_pk_mul_f32 v[36:37], v[86:87], v[36:37] op_sel:[1,0]
	v_pk_mul_f32 v[38:39], v[86:87], v[38:39] op_sel:[1,0]
	v_pk_mul_f32 v[40:41], v[86:87], v[40:41] op_sel:[1,0]
	v_pk_mul_f32 v[42:43], v[86:87], v[42:43] op_sel:[1,0]
	v_pk_mul_f32 v[36:37], v[36:37], v[44:45]
	v_pk_mul_f32 v[38:39], v[38:39], v[46:47]
	v_pk_mul_f32 v[40:41], v[40:41], v[48:49]
	v_pk_mul_f32 v[42:43], v[42:43], v[50:51]
	v_pk_mul_f32 v[98:99], v[36:37], v[98:99]
	v_pk_mul_f32 v[106:107], v[38:39], v[106:107]
	v_pk_mul_f32 v[114:115], v[40:41], v[114:115]
	v_pk_mul_f32 v[122:123], v[42:43], v[122:123]
	v_pk_mul_f32 v[130:131], v[130:131], v[36:37]
	v_pk_mul_f32 v[138:139], v[138:139], v[38:39]
	v_pk_mul_f32 v[146:147], v[146:147], v[40:41]
	v_pk_mul_f32 v[154:155], v[154:155], v[42:43]
	v_pk_mul_f32 v[96:97], v[98:99], v[96:97]
	v_pk_mul_f32 v[104:105], v[106:107], v[104:105]
	v_pk_mul_f32 v[112:113], v[114:115], v[112:113]
	v_pk_mul_f32 v[120:121], v[122:123], v[120:121]
	v_pk_mul_f32 v[128:129], v[128:129], v[98:99]
	v_pk_mul_f32 v[136:137], v[136:137], v[106:107]
	v_pk_mul_f32 v[144:145], v[144:145], v[114:115]
	v_pk_mul_f32 v[152:153], v[152:153], v[122:123]
	v_pk_mul_f32 v[94:95], v[96:97], v[94:95]
	v_pk_mul_f32 v[102:103], v[104:105], v[102:103]
	v_pk_mul_f32 v[110:111], v[112:113], v[110:111]
	v_pk_mul_f32 v[118:119], v[120:121], v[118:119]
	v_pk_mul_f32 v[126:127], v[126:127], v[96:97]
	v_pk_mul_f32 v[134:135], v[134:135], v[104:105]
	v_pk_mul_f32 v[142:143], v[142:143], v[112:113]
	v_pk_mul_f32 v[150:151], v[150:151], v[120:121]
	v_pk_mul_f32 v[124:125], v[124:125], v[94:95]
	v_pk_mul_f32 v[132:133], v[132:133], v[102:103]
	v_pk_mul_f32 v[140:141], v[140:141], v[110:111]
	v_pk_mul_f32 v[148:149], v[148:149], v[118:119]
	v_cvt_pk_bf16_f32 v52, v124, v126
	v_cvt_pk_bf16_f32 v53, v128, v130
	v_cvt_pk_bf16_f32 v54, v125, v127
	v_cvt_pk_bf16_f32 v55, v129, v131
	v_cvt_pk_bf16_f32 v56, v132, v134
	v_cvt_pk_bf16_f32 v57, v136, v138
	v_cvt_pk_bf16_f32 v58, v133, v135
	v_cvt_pk_bf16_f32 v59, v137, v139
	v_cvt_pk_bf16_f32 v60, v140, v142
	v_cvt_pk_bf16_f32 v61, v144, v146
	v_cvt_pk_bf16_f32 v62, v141, v143
	v_cvt_pk_bf16_f32 v63, v145, v147
	v_cvt_pk_bf16_f32 v64, v148, v150
	v_cvt_pk_bf16_f32 v65, v152, v154
	v_cvt_pk_bf16_f32 v66, v149, v151
	v_cvt_pk_bf16_f32 v67, v153, v155
	v_mul_f32_e32 v87, v87, v164
	v_cmp_gt_f32_e32 vcc, 7, v87
	s_cmp_eq_u64 vcc, exec
	s_cselect_b64 s[24:25], -1, 0
	s_waitcnt lgkmcnt(6)
	v_mfma_f32_32x32x16_bf16 v[20:35], v[202:205], v[52:55], v[20:35]
	s_waitcnt lgkmcnt(4)
	v_mfma_f32_32x32x16_bf16 v[4:19], v[206:209], v[52:55], v[4:19]
	ds_read_b64_tr_b16 v[202:203], v86 offset:12288
	ds_read_b64_tr_b16 v[204:205], v86 offset:13312
	ds_read_b64_tr_b16 v[206:207], v165 offset:12288
	ds_read_b64_tr_b16 v[208:209], v165 offset:13312
	s_waitcnt lgkmcnt(6)
	v_mfma_f32_32x32x16_bf16 v[20:35], v[210:213], v[56:59], v[20:35]
	s_waitcnt lgkmcnt(4)
	v_mfma_f32_32x32x16_bf16 v[4:19], v[214:217], v[56:59], v[4:19]
	ds_read_b64_tr_b16 v[210:211], v86 offset:14336
	ds_read_b64_tr_b16 v[212:213], v86 offset:15360
	ds_read_b64_tr_b16 v[214:215], v165 offset:14336
	ds_read_b64_tr_b16 v[216:217], v165 offset:15360
	s_waitcnt lgkmcnt(6)
	v_mfma_f32_32x32x16_bf16 v[20:35], v[202:205], v[60:63], v[20:35]
	s_waitcnt lgkmcnt(4)
	v_mfma_f32_32x32x16_bf16 v[4:19], v[206:209], v[60:63], v[4:19]
	s_waitcnt lgkmcnt(2)
	v_mfma_f32_32x32x16_bf16 v[20:35], v[210:213], v[64:67], v[20:35]
	s_waitcnt lgkmcnt(0)
	v_mfma_f32_32x32x16_bf16 v[4:19], v[214:217], v[64:67], v[4:19]
	s_branch .LBB0_629
